# baseline (speedup 1.0000x reference)
; #define WAIT_V(n) asm volatile("s_waitcnt vmcnt(%0)" ::"n"(n) : "memory")
; template <int DQK, bool ALIBI>
; DEVI void attn_pass(const AttnArgs& a, f32x16 (&o)[4], const int tid_) {
;     ...
;   GLDS_KV(0, tile_of(0)); WAIT_V(0); __syncthreads();
;   for (int n = 0; n < cnt; ++n) {
;     const int buf = n & 1;
;     const int j = tile_of(n);
;     const bool last = (j == NT - 1);
;     if (n + 1 < cnt) GLDS_KV(buf ^ 1, tile_of(n + 1));
;     if (wactive) {
;       f32x16 p0 = f32x16{}, p1 = f32x16{};
;       const unsigned char* Ks = K_lds + buf * SHM_K + r32 * KPITCH;
;       const int key = KKEY(r32);
;     ...
;       if constexpr (DQK == 128 || DQK == 64 || DQK == 192) {
;         constexpr int NG4 = DQK / 64;
;         bf16x8 ka[4][2], kb[4][2];
; #pragma unroll
;         for (int s = 0; s < 4; ++s) { ka[s][0] = *(const bf16x8*)(Ks + KCB(s)); ka[s][1] = *(const bf16x8*)(Ks + 32 * KPITCH + KCB(s)); }
.LBB0_211:
	s_mov_b32 s13, s3
	s_and_b32 s42, s3, 1
	s_mul_i32 s35, s42, 0x6000
	v_add_u32_e32 v74, s35, v198
	v_add_u32_e32 v168, v74, v202
	v_add_u32_e32 v169, v74, v203
	v_add_u32_e32 v240, v74, v200
	v_add_u32_e32 v241, v74, v201
	ds_read_b128 v[66:69], v168 offset:32768
	ds_read_b128 v[70:73], v168 offset:45056
	ds_read_b128 v[204:207], v169 offset:32768
	ds_read_b128 v[208:211], v169 offset:45056
	ds_read_b128 v[212:215], v240 offset:32768
	ds_read_b128 v[216:219], v240 offset:45056
	ds_read_b128 v[220:223], v241 offset:32768
	ds_read_b128 v[224:227], v241 offset:45056
	s_add_i32 s3, s3, 1
	s_cmp_ge_u32 s13, s7
	s_cbranch_scc1 .LBB0_216
	s_cmp_gt_u32 s7, s3
	s_mov_b64 s[34:35], -1
	s_cbranch_scc1 .LBB0_214
	s_xor_b32 s13, s42, 1
	s_mulk_i32 s13, 0x6000
	v_add_u32_e32 v228, s13, v197
	v_add_u32_e32 v229, 0x8000, v228
	s_mov_b64 s[34:35], 0
	v_readfirstlane_b32 s13, v229
	v_add_u32_e32 v229, 0xa000, v228
	s_mov_b32 m0, s13
	v_readfirstlane_b32 s13, v229
	v_add_u32_e32 v228, 0xc000, v228
	global_load_lds_dwordx4 v[158:159], off
	s_mov_b32 m0, s13
	v_readfirstlane_b32 s13, v228
	global_load_lds_dwordx4 v[160:161], off
	s_mov_b32 m0, s13
	s_lshl_b32 s13, s42, 14
	s_xor_b32 s13, s13, 0x4000
	v_add_u32_e32 v228, s13, v197
	global_load_lds_dwordx4 v[162:163], off
	v_readfirstlane_b32 s13, v228
	v_add_u32_e32 v228, 0x2000, v228
	s_mov_b32 m0, s13
	v_readfirstlane_b32 s13, v228
	global_load_lds_dwordx4 v[164:165], off
	s_mov_b32 m0, s13
	s_nop 0
	global_load_lds_dwordx4 v[166:167], off

; #define SBAR() __builtin_amdgcn_sched_barrier(0)
; template <bool ALIBI, bool LAST>
; DEVI void softmax_tile(f32x16& p0, f32x16& p1, const float C, const float nslope2, const float dbase, float& m_reg, float& l_reg, float& alpha,
;                        bf16x8& pa0, bf16x8& pa1, bf16x8& pa2, bf16x8& pa3) {
;     ...
;   float pmax = p0[0];
; #pragma unroll
;   for (int r = 1; r < 16; ++r) pmax = fmaxf(pmax, p0[r]);
;   if constexpr (!LAST) {
; #pragma unroll
;     for (int r = 0; r < 16; ++r) pmax = fmaxf(pmax, p1[r]);
;   }
;   { auto rr = __builtin_amdgcn_permlane32_swap(__float_as_uint(pmax), __float_as_uint(pmax), false, false);
;     pmax = fmaxf(__uint_as_float(rr[0]), __uint_as_float(rr[1])); }
;   const float THRU = 8.f * LOG2E / C;
;   const float CU = C;
;   if (__builtin_expect(__all(pmax - m_reg <= THRU), 1)) { alpha = 1.f; }
;   else { float mn = fmaxf(m_reg, pmax); alpha = __builtin_amdgcn_exp2f((m_reg - mn) * CU); m_reg = mn; }
; template <int DQK, bool ALIBI>
; DEVI void attn_pass(const AttnArgs& a, f32x16 (&o)[4], const int tid_) {
;     ...
;     if (wactive) {
;       f32x16 p0 = f32x16{}, p1 = f32x16{};
;       const unsigned char* Ks = K_lds + buf * SHM_K + r32 * KPITCH;
;       const int key = KKEY(r32);
;     ...
;       if constexpr (DQK == 128 || DQK == 64 || DQK == 192) {
;         constexpr int NG4 = DQK / 64;
;         bf16x8 ka[4][2], kb[4][2];
; #pragma unroll
;         for (int s = 0; s < 4; ++s) { ka[s][0] = *(const bf16x8*)(Ks + KCB(s)); ka[s][1] = *(const bf16x8*)(Ks + 32 * KPITCH + KCB(s)); }
;         SBAR();
; #pragma unroll
;         for (int g = 0; g < NG4; ++g) {
;           if (g + 1 < NG4) {
; #pragma unroll
;             for (int s = 0; s < 4; ++s) { const int d1 = (g + 1) * 4 + s;
;               if (g & 1) { ka[s][0] = *(const bf16x8*)(Ks + KCB(d1)); ka[s][1] = *(const bf16x8*)(Ks + 32 * KPITCH + KCB(d1)); }
;               else       { kb[s][0] = *(const bf16x8*)(Ks + KCB(d1)); kb[s][1] = *(const bf16x8*)(Ks + 32 * KPITCH + KCB(d1)); } }
;           }
; #pragma unroll
;           for (int s = 0; s < 4; ++s) { const int d0 = g * 4 + s;
;             p0 = __builtin_amdgcn_mfma_f32_32x32x16_bf16((g & 1) ? kb[s][0] : ka[s][0], qr[d0], p0, 0, 0, 0);
;             p1 = __builtin_amdgcn_mfma_f32_32x32x16_bf16((g & 1) ? kb[s][1] : ka[s][1], qr[d0], p1, 0, 0, 0); }
;           SBAR();
.LBB0_216:
	s_and_saveexec_b64 s[34:35], s[4:5]
	s_cbranch_execz .LBB0_210
	s_waitcnt lgkmcnt(6)
	v_mfma_f32_32x32x16_bf16 v[82:97], v[66:69], v[126:129], 0
	v_mfma_f32_32x32x16_bf16 v[66:81], v[70:73], v[126:129], 0
	s_waitcnt lgkmcnt(4)
	v_mfma_f32_32x32x16_bf16 v[82:97], v[204:207], v[122:125], v[82:97]
	v_mfma_f32_32x32x16_bf16 v[66:81], v[208:211], v[122:125], v[66:81]
	s_waitcnt lgkmcnt(2)
	v_mfma_f32_32x32x16_bf16 v[82:97], v[212:215], v[118:121], v[82:97]
	v_mfma_f32_32x32x16_bf16 v[66:81], v[216:219], v[118:121], v[66:81]
	s_waitcnt lgkmcnt(0)
	v_mfma_f32_32x32x16_bf16 v[82:97], v[220:223], v[114:117], v[82:97]
	ds_read_b128 v[204:207], v168 offset:32896
	ds_read_b128 v[208:211], v168 offset:45184
	ds_read_b128 v[212:215], v169 offset:32896
	ds_read_b128 v[216:219], v169 offset:45184
	ds_read_b128 v[220:223], v240 offset:32896
	ds_read_b128 v[228:231], v240 offset:45184
	ds_read_b128 v[232:235], v241 offset:32896
	ds_read_b128 v[236:239], v241 offset:45184
	v_mfma_f32_32x32x16_bf16 v[66:81], v[224:227], v[114:117], v[66:81]
	s_waitcnt lgkmcnt(6)
	v_mfma_f32_32x32x16_bf16 v[82:97], v[204:207], v[110:113], v[82:97]
	v_mfma_f32_32x32x16_bf16 v[66:81], v[208:211], v[110:113], v[66:81]
	s_waitcnt lgkmcnt(4)
	v_mfma_f32_32x32x16_bf16 v[82:97], v[212:215], v[106:109], v[82:97]
	v_mfma_f32_32x32x16_bf16 v[66:81], v[216:219], v[106:109], v[66:81]
	s_waitcnt lgkmcnt(2)
	v_mfma_f32_32x32x16_bf16 v[82:97], v[220:223], v[102:105], v[82:97]
	v_mfma_f32_32x32x16_bf16 v[66:81], v[228:231], v[102:105], v[66:81]
	s_waitcnt lgkmcnt(0)
	v_mfma_f32_32x32x16_bf16 v[82:97], v[232:235], v[98:101], v[82:97]
	ds_read_b128 v[204:207], v168 offset:33024
	ds_read_b128 v[208:211], v168 offset:45312
	ds_read_b128 v[212:215], v169 offset:33024
	ds_read_b128 v[216:219], v169 offset:45312
	ds_read_b128 v[220:223], v240 offset:33024
	ds_read_b128 v[224:227], v240 offset:45312
	ds_read_b128 v[228:231], v241 offset:33024
	ds_read_b128 v[232:235], v241 offset:45312
	v_mfma_f32_32x32x16_bf16 v[66:81], v[236:239], v[98:101], v[66:81]
	s_waitcnt lgkmcnt(6)
	v_mfma_f32_32x32x16_bf16 v[82:97], v[204:207], v[134:137], v[82:97]
	v_mfma_f32_32x32x16_bf16 v[66:81], v[208:211], v[134:137], v[66:81]
	s_waitcnt lgkmcnt(4)
	v_mfma_f32_32x32x16_bf16 v[82:97], v[212:215], v[142:145], v[82:97]
	v_mfma_f32_32x32x16_bf16 v[66:81], v[216:219], v[142:145], v[66:81]
	s_waitcnt lgkmcnt(2)
	v_mfma_f32_32x32x16_bf16 v[82:97], v[220:223], v[130:133], v[82:97]
	v_mfma_f32_32x32x16_bf16 v[66:81], v[224:227], v[130:133], v[66:81]
	s_waitcnt lgkmcnt(0)
	v_mfma_f32_32x32x16_bf16 v[82:97], v[228:231], v[138:141], v[82:97]
	v_mfma_f32_32x32x16_bf16 v[66:81], v[232:235], v[138:141], v[66:81]
	v_lshl_add_u32 v236, s42, 14, v196
	ds_read_b64_tr_b16 v[204:205], v236 offset:0x0
	ds_read_b64_tr_b16 v[206:207], v236 offset:0x800
	ds_read_b64_tr_b16 v[208:209], v236 offset:0x200
	ds_read_b64_tr_b16 v[210:211], v236 offset:0xa00
	ds_read_b64_tr_b16 v[212:213], v236 offset:0x400
	ds_read_b64_tr_b16 v[214:215], v236 offset:0xc00
	ds_read_b64_tr_b16 v[216:217], v236 offset:0x600
	ds_read_b64_tr_b16 v[218:219], v236 offset:0xe00
	s_nop 1
	v_max3_f32 v168, v82, v83, v84
	v_max3_f32 v168, v168, v85, v86
	v_max3_f32 v168, v168, v87, v88
	v_max3_f32 v168, v168, v89, v90
	v_max3_f32 v168, v168, v91, v92
	v_max3_f32 v168, v168, v93, v94
	v_max3_f32 v168, v168, v95, v96
	v_max3_f32 v168, v168, v97, v66
	v_max3_f32 v168, v168, v67, v68
	v_max3_f32 v168, v168, v69, v70
	v_max3_f32 v168, v168, v71, v72
	v_max3_f32 v168, v168, v73, v74
	v_max3_f32 v168, v168, v75, v76
	v_max3_f32 v168, v168, v77, v78
	v_max3_f32 v168, v168, v79, v80
	v_max_f32_e32 v168, v168, v81
	v_mov_b32_e32 v169, v168
	s_nop 1
	v_permlane32_swap_b32_e32 v168, v169
	v_max_f32_e32 v168, v168, v169
	v_sub_f32_e32 v169, v168, v199
	v_cmp_ge_f32_e32 vcc, s17, v169
	s_cmp_eq_u64 vcc, exec
	s_cbranch_scc0 .Lmy_B_slow
	v_mov_b32_e32 v168, 1.0
